# v63 + GEMM K-loops: pointer/counter updates and the exit compare moved ahead of the loop-closing barrier
# baseline (speedup 1.0000x reference)
.LBB0_211:
	s_add_i32 s73, s58, 2
	s_add_u32 s74, s56, 0x80
	s_addc_u32 s59, s57, 0
	s_add_i32 s78, 0, 0x10000
	s_cmp_eq_u32 s63, s58
	s_cselect_b32 s59, s51, s59
	s_cselect_b32 s58, s55, s74
	v_add_u32_e32 v0, s78, v146
	s_cselect_b32 s75, s45, s72
	s_cselect_b32 s74, s44, s67
	s_add_i32 s80, 0, 0x14000
	ds_read_b128 v[148:151], v0
	ds_read_b128 v[152:155], v0 offset:1024
	ds_read_b128 v[156:159], v0 offset:2048
	ds_read_b128 v[160:163], v0 offset:3072
	v_add_u32_e32 v0, s80, v146
	ds_read_b128 v[164:167], v0
	ds_read_b128 v[168:171], v0 offset:1024
	ds_read_b128 v[172:175], v0 offset:2048
	ds_read_b128 v[176:179], v0 offset:3072
	s_mov_b32 m0, s31
	v_lshl_add_u64 v[142:143], s[56:57], 0, v[136:137]
	global_load_lds_dwordx4 v[142:143], off
	v_lshl_add_u64 v[142:143], s[56:57], 0, v[132:133]
	s_mov_b32 m0, s53
	s_nop 0
	global_load_lds_dwordx4 v[142:143], off
	v_lshl_add_u64 v[142:143], s[56:57], 0, v[138:139]
	s_add_i32 m0, s27, 0xc000
	s_nop 0
	global_load_lds_dwordx4 v[142:143], off
	v_lshl_add_u64 v[142:143], s[56:57], 0, v[140:141]
	s_add_i32 m0, s27, 0xe000
	s_nop 0
	global_load_lds_dwordx4 v[142:143], off
	ds_read_b128 v[180:183], v147
	ds_read_b128 v[184:187], v147 offset:1024
	ds_read_b128 v[200:203], v147 offset:2048
	ds_read_b128 v[204:207], v147 offset:3072
	ds_read_b128 v[208:211], v147 offset:4096
	ds_read_b128 v[212:215], v147 offset:5120
	ds_read_b128 v[216:219], v147 offset:6144
	ds_read_b128 v[220:223], v147 offset:7168
	s_waitcnt vmcnt(8)
	s_waitcnt lgkmcnt(0)
	s_barrier
	s_setprio 1
	s_waitcnt lgkmcnt(0)
	v_mfma_f32_16x16x32_bf16 v[122:125], v[148:151], v[180:183], v[122:125]
	v_mfma_f32_16x16x32_bf16 v[126:129], v[156:159], v[180:183], v[126:129]
	v_mfma_f32_16x16x32_bf16 v[110:113], v[148:151], v[200:203], v[110:113]
	v_mfma_f32_16x16x32_bf16 v[106:109], v[156:159], v[200:203], v[106:109]
	v_mfma_f32_16x16x32_bf16 v[94:97], v[148:151], v[208:211], v[94:97]
	v_mfma_f32_16x16x32_bf16 v[90:93], v[156:159], v[208:211], v[90:93]
	v_mfma_f32_16x16x32_bf16 v[78:81], v[148:151], v[216:219], v[78:81]
	v_mfma_f32_16x16x32_bf16 v[74:77], v[156:159], v[216:219], v[74:77]
	v_mfma_f32_16x16x32_bf16 v[122:125], v[152:155], v[184:187], v[122:125]
	v_mfma_f32_16x16x32_bf16 v[126:129], v[160:163], v[184:187], v[126:129]
	v_mfma_f32_16x16x32_bf16 v[110:113], v[152:155], v[204:207], v[110:113]
	v_mfma_f32_16x16x32_bf16 v[106:109], v[160:163], v[204:207], v[106:109]
	v_mfma_f32_16x16x32_bf16 v[94:97], v[152:155], v[212:215], v[94:97]
	v_mfma_f32_16x16x32_bf16 v[90:93], v[160:163], v[212:215], v[90:93]
	v_mfma_f32_16x16x32_bf16 v[78:81], v[152:155], v[220:223], v[78:81]
	v_mfma_f32_16x16x32_bf16 v[74:77], v[160:163], v[220:223], v[74:77]
	s_setprio 0
	s_setprio 1
	v_mfma_f32_16x16x32_bf16 v[118:121], v[164:167], v[180:183], v[118:121]
	v_mfma_f32_16x16x32_bf16 v[114:117], v[172:175], v[180:183], v[114:117]
	v_mfma_f32_16x16x32_bf16 v[102:105], v[164:167], v[200:203], v[102:105]
	v_mfma_f32_16x16x32_bf16 v[98:101], v[172:175], v[200:203], v[98:101]
	v_mfma_f32_16x16x32_bf16 v[86:89], v[164:167], v[208:211], v[86:89]
	v_mfma_f32_16x16x32_bf16 v[82:85], v[172:175], v[208:211], v[82:85]
	v_mfma_f32_16x16x32_bf16 v[70:73], v[164:167], v[216:219], v[70:73]
	v_mfma_f32_16x16x32_bf16 v[66:69], v[172:175], v[216:219], v[66:69]
	v_mfma_f32_16x16x32_bf16 v[118:121], v[168:171], v[184:187], v[118:121]
	v_mfma_f32_16x16x32_bf16 v[114:117], v[176:179], v[184:187], v[114:117]
	v_mfma_f32_16x16x32_bf16 v[102:105], v[168:171], v[204:207], v[102:105]
	v_mfma_f32_16x16x32_bf16 v[98:101], v[176:179], v[204:207], v[98:101]
	v_mfma_f32_16x16x32_bf16 v[86:89], v[168:171], v[212:215], v[86:89]
	v_mfma_f32_16x16x32_bf16 v[82:85], v[176:179], v[212:215], v[82:85]
	v_mfma_f32_16x16x32_bf16 v[70:73], v[168:171], v[220:223], v[70:73]
	v_mfma_f32_16x16x32_bf16 v[66:69], v[176:179], v[220:223], v[66:69]
	s_setprio 0
	s_barrier
	s_add_i32 s78, s78, s5
	v_lshl_add_u64 v[142:143], s[74:75], 0, v[134:135]
	s_mov_b32 m0, s78
	ds_read_b128 v[180:183], v147 offset:16384
	ds_read_b128 v[184:187], v147 offset:17408
	ds_read_b128 v[200:203], v147 offset:18432
	ds_read_b128 v[204:207], v147 offset:19456
	ds_read_b128 v[208:211], v147 offset:20480
	ds_read_b128 v[212:215], v147 offset:21504
	ds_read_b128 v[216:219], v147 offset:22528
	ds_read_b128 v[220:223], v147 offset:23552
	global_load_lds_dwordx4 v[142:143], off
	s_add_i32 m0, s78, 0x2000
	v_lshl_add_u64 v[188:189], s[74:75], 0, v[130:131]
	s_add_u32 s74, s74, s6
	s_addc_u32 s75, s75, s7
	s_add_i32 s78, s80, s5
	global_load_lds_dwordx4 v[188:189], off
	v_lshl_add_u64 v[224:225], s[74:75], 0, v[134:135]
	s_mov_b32 m0, s78
	v_lshl_add_u64 v[226:227], s[74:75], 0, v[130:131]
	global_load_lds_dwordx4 v[224:225], off
	s_add_i32 m0, s78, 0x2000
	v_lshl_add_u64 v[228:229], s[58:59], 0, v[136:137]
	global_load_lds_dwordx4 v[226:227], off
	v_lshl_add_u64 v[230:231], s[58:59], 0, v[132:133]
	s_waitcnt vmcnt(6)
	s_waitcnt lgkmcnt(0)
	s_barrier
	s_setprio 1
	s_waitcnt lgkmcnt(0)
	v_mfma_f32_16x16x32_bf16 v[62:65], v[148:151], v[180:183], v[62:65]
	v_mfma_f32_16x16x32_bf16 v[58:61], v[156:159], v[180:183], v[58:61]
	v_mfma_f32_16x16x32_bf16 v[46:49], v[148:151], v[200:203], v[46:49]
	v_mfma_f32_16x16x32_bf16 v[42:45], v[156:159], v[200:203], v[42:45]
	v_mfma_f32_16x16x32_bf16 v[30:33], v[148:151], v[208:211], v[30:33]
	v_mfma_f32_16x16x32_bf16 v[26:29], v[156:159], v[208:211], v[26:29]
	v_mfma_f32_16x16x32_bf16 v[14:17], v[148:151], v[216:219], v[14:17]
	v_mfma_f32_16x16x32_bf16 v[10:13], v[156:159], v[216:219], v[10:13]
	v_mfma_f32_16x16x32_bf16 v[62:65], v[152:155], v[184:187], v[62:65]
	v_mfma_f32_16x16x32_bf16 v[58:61], v[160:163], v[184:187], v[58:61]
	v_mfma_f32_16x16x32_bf16 v[46:49], v[152:155], v[204:207], v[46:49]
	v_mfma_f32_16x16x32_bf16 v[42:45], v[160:163], v[204:207], v[42:45]
	v_mfma_f32_16x16x32_bf16 v[30:33], v[152:155], v[212:215], v[30:33]
	v_mfma_f32_16x16x32_bf16 v[26:29], v[160:163], v[212:215], v[26:29]
	v_mfma_f32_16x16x32_bf16 v[14:17], v[152:155], v[220:223], v[14:17]
	v_mfma_f32_16x16x32_bf16 v[10:13], v[160:163], v[220:223], v[10:13]
	s_setprio 0
	s_setprio 1
	v_mfma_f32_16x16x32_bf16 v[54:57], v[164:167], v[180:183], v[54:57]
	v_mfma_f32_16x16x32_bf16 v[50:53], v[172:175], v[180:183], v[50:53]
	v_mfma_f32_16x16x32_bf16 v[38:41], v[164:167], v[200:203], v[38:41]
	v_mfma_f32_16x16x32_bf16 v[34:37], v[172:175], v[200:203], v[34:37]
	v_mfma_f32_16x16x32_bf16 v[22:25], v[164:167], v[208:211], v[22:25]
	v_mfma_f32_16x16x32_bf16 v[18:21], v[172:175], v[208:211], v[18:21]
	v_mfma_f32_16x16x32_bf16 v[6:9], v[164:167], v[216:219], v[6:9]
	v_mfma_f32_16x16x32_bf16 v[2:5], v[172:175], v[216:219], v[2:5]
	v_mfma_f32_16x16x32_bf16 v[54:57], v[168:171], v[184:187], v[54:57]
	v_mfma_f32_16x16x32_bf16 v[50:53], v[176:179], v[184:187], v[50:53]
	v_mfma_f32_16x16x32_bf16 v[38:41], v[168:171], v[204:207], v[38:41]
	v_mfma_f32_16x16x32_bf16 v[34:37], v[176:179], v[204:207], v[34:37]
	v_mfma_f32_16x16x32_bf16 v[22:25], v[168:171], v[212:215], v[22:25]
	v_mfma_f32_16x16x32_bf16 v[18:21], v[176:179], v[212:215], v[18:21]
	v_mfma_f32_16x16x32_bf16 v[6:9], v[168:171], v[220:223], v[6:9]
	v_mfma_f32_16x16x32_bf16 v[2:5], v[176:179], v[220:223], v[2:5]
	s_setprio 0
	s_barrier
	s_add_i32 s74, 0, 0x18000
	v_add_u32_e32 v0, s74, v146
	s_add_i32 s75, 0, 0x1c000
	ds_read_b128 v[148:151], v0
	ds_read_b128 v[152:155], v0 offset:1024
	ds_read_b128 v[156:159], v0 offset:2048
	ds_read_b128 v[160:163], v0 offset:3072
	v_add_u32_e32 v0, s75, v146
	ds_read_b128 v[164:167], v0
	ds_read_b128 v[168:171], v0 offset:1024
	ds_read_b128 v[172:175], v0 offset:2048
	ds_read_b128 v[176:179], v0 offset:3072
	s_add_u32 s58, s58, s2
	s_addc_u32 s59, s59, s3
	s_mov_b32 m0, s27
	v_lshl_add_u64 v[232:233], s[58:59], 0, v[136:137]
	s_nop 0
	global_load_lds_dwordx4 v[228:229], off
	s_mov_b32 m0, s28
	s_nop 0
	global_load_lds_dwordx4 v[230:231], off
	s_mov_b32 m0, s29
	s_nop 0
	global_load_lds_dwordx4 v[232:233], off
	v_lshl_add_u64 v[232:233], s[58:59], 0, v[132:133]
	s_mov_b32 m0, s30
	s_nop 0
	global_load_lds_dwordx4 v[232:233], off
	ds_read_b128 v[180:183], v147 offset:32768
	ds_read_b128 v[184:187], v147 offset:33792
	ds_read_b128 v[200:203], v147 offset:34816
	ds_read_b128 v[204:207], v147 offset:35840
	ds_read_b128 v[208:211], v147 offset:36864
	ds_read_b128 v[212:215], v147 offset:37888
	ds_read_b128 v[216:219], v147 offset:38912
	ds_read_b128 v[220:223], v147 offset:39936
	s_waitcnt vmcnt(8)
	s_waitcnt lgkmcnt(0)
	s_barrier
	s_setprio 1
	s_waitcnt lgkmcnt(0)
	v_mfma_f32_16x16x32_bf16 v[122:125], v[148:151], v[180:183], v[122:125]
	v_mfma_f32_16x16x32_bf16 v[126:129], v[156:159], v[180:183], v[126:129]
	v_mfma_f32_16x16x32_bf16 v[110:113], v[148:151], v[200:203], v[110:113]
	v_mfma_f32_16x16x32_bf16 v[106:109], v[156:159], v[200:203], v[106:109]
	v_mfma_f32_16x16x32_bf16 v[94:97], v[148:151], v[208:211], v[94:97]
	v_mfma_f32_16x16x32_bf16 v[90:93], v[156:159], v[208:211], v[90:93]
	v_mfma_f32_16x16x32_bf16 v[78:81], v[148:151], v[216:219], v[78:81]
	v_mfma_f32_16x16x32_bf16 v[74:77], v[156:159], v[216:219], v[74:77]
	v_mfma_f32_16x16x32_bf16 v[122:125], v[152:155], v[184:187], v[122:125]
	v_mfma_f32_16x16x32_bf16 v[126:129], v[160:163], v[184:187], v[126:129]
	v_mfma_f32_16x16x32_bf16 v[110:113], v[152:155], v[204:207], v[110:113]
	v_mfma_f32_16x16x32_bf16 v[106:109], v[160:163], v[204:207], v[106:109]
	v_mfma_f32_16x16x32_bf16 v[94:97], v[152:155], v[212:215], v[94:97]
	v_mfma_f32_16x16x32_bf16 v[90:93], v[160:163], v[212:215], v[90:93]
	v_mfma_f32_16x16x32_bf16 v[78:81], v[152:155], v[220:223], v[78:81]
	v_mfma_f32_16x16x32_bf16 v[74:77], v[160:163], v[220:223], v[74:77]
	s_setprio 0
	s_setprio 1
	v_mfma_f32_16x16x32_bf16 v[118:121], v[164:167], v[180:183], v[118:121]
	v_mfma_f32_16x16x32_bf16 v[114:117], v[172:175], v[180:183], v[114:117]
	v_mfma_f32_16x16x32_bf16 v[102:105], v[164:167], v[200:203], v[102:105]
	v_mfma_f32_16x16x32_bf16 v[98:101], v[172:175], v[200:203], v[98:101]
	v_mfma_f32_16x16x32_bf16 v[86:89], v[164:167], v[208:211], v[86:89]
	v_mfma_f32_16x16x32_bf16 v[82:85], v[172:175], v[208:211], v[82:85]
	v_mfma_f32_16x16x32_bf16 v[70:73], v[164:167], v[216:219], v[70:73]
	v_mfma_f32_16x16x32_bf16 v[66:69], v[172:175], v[216:219], v[66:69]
	v_mfma_f32_16x16x32_bf16 v[118:121], v[168:171], v[184:187], v[118:121]
	v_mfma_f32_16x16x32_bf16 v[114:117], v[176:179], v[184:187], v[114:117]
	v_mfma_f32_16x16x32_bf16 v[102:105], v[168:171], v[204:207], v[102:105]
	v_mfma_f32_16x16x32_bf16 v[98:101], v[176:179], v[204:207], v[98:101]
	v_mfma_f32_16x16x32_bf16 v[86:89], v[168:171], v[212:215], v[86:89]
	v_mfma_f32_16x16x32_bf16 v[82:85], v[176:179], v[212:215], v[82:85]
	v_mfma_f32_16x16x32_bf16 v[70:73], v[168:171], v[220:223], v[70:73]
	v_mfma_f32_16x16x32_bf16 v[66:69], v[176:179], v[220:223], v[66:69]
	s_setprio 0
	s_barrier
	s_add_i32 s58, s74, s5
	v_lshl_add_u64 v[142:143], v[142:143], 0, s[24:25]
	s_mov_b32 m0, s58
	ds_read_b128 v[180:183], v147 offset:49152
	ds_read_b128 v[184:187], v147 offset:50176
	ds_read_b128 v[200:203], v147 offset:51200
	ds_read_b128 v[204:207], v147 offset:52224
	ds_read_b128 v[208:211], v147 offset:53248
	ds_read_b128 v[212:215], v147 offset:54272
	ds_read_b128 v[216:219], v147 offset:55296
	ds_read_b128 v[220:223], v147 offset:56320
	global_load_lds_dwordx4 v[142:143], off
	v_lshl_add_u64 v[142:143], v[188:189], 0, s[24:25]
	s_add_i32 m0, s58, 0x2000
	s_add_i32 s58, s75, s5
	global_load_lds_dwordx4 v[142:143], off
	v_lshl_add_u64 v[142:143], v[224:225], 0, s[24:25]
	s_mov_b32 m0, s58
	s_nop 0
	global_load_lds_dwordx4 v[142:143], off
	v_lshl_add_u64 v[142:143], v[226:227], 0, s[24:25]
	s_add_i32 m0, s58, 0x2000
	s_nop 0
	global_load_lds_dwordx4 v[142:143], off
	s_waitcnt vmcnt(6)
	s_waitcnt lgkmcnt(0)
	s_barrier
	s_setprio 1
	s_waitcnt lgkmcnt(0)
	v_mfma_f32_16x16x32_bf16 v[62:65], v[148:151], v[180:183], v[62:65]
	v_mfma_f32_16x16x32_bf16 v[58:61], v[156:159], v[180:183], v[58:61]
	v_mfma_f32_16x16x32_bf16 v[46:49], v[148:151], v[200:203], v[46:49]
	v_mfma_f32_16x16x32_bf16 v[42:45], v[156:159], v[200:203], v[42:45]
	v_mfma_f32_16x16x32_bf16 v[30:33], v[148:151], v[208:211], v[30:33]
	v_mfma_f32_16x16x32_bf16 v[26:29], v[156:159], v[208:211], v[26:29]
	v_mfma_f32_16x16x32_bf16 v[14:17], v[148:151], v[216:219], v[14:17]
	v_mfma_f32_16x16x32_bf16 v[10:13], v[156:159], v[216:219], v[10:13]
	v_mfma_f32_16x16x32_bf16 v[62:65], v[152:155], v[184:187], v[62:65]
	v_mfma_f32_16x16x32_bf16 v[58:61], v[160:163], v[184:187], v[58:61]
	v_mfma_f32_16x16x32_bf16 v[46:49], v[152:155], v[204:207], v[46:49]
	v_mfma_f32_16x16x32_bf16 v[42:45], v[160:163], v[204:207], v[42:45]
	v_mfma_f32_16x16x32_bf16 v[30:33], v[152:155], v[212:215], v[30:33]
	v_mfma_f32_16x16x32_bf16 v[26:29], v[160:163], v[212:215], v[26:29]
	v_mfma_f32_16x16x32_bf16 v[14:17], v[152:155], v[220:223], v[14:17]
	v_mfma_f32_16x16x32_bf16 v[10:13], v[160:163], v[220:223], v[10:13]
	s_setprio 0
	s_setprio 1
	v_mfma_f32_16x16x32_bf16 v[54:57], v[164:167], v[180:183], v[54:57]
	v_mfma_f32_16x16x32_bf16 v[50:53], v[172:175], v[180:183], v[50:53]
	v_mfma_f32_16x16x32_bf16 v[38:41], v[164:167], v[200:203], v[38:41]
	v_mfma_f32_16x16x32_bf16 v[34:37], v[172:175], v[200:203], v[34:37]
	v_mfma_f32_16x16x32_bf16 v[22:25], v[164:167], v[208:211], v[22:25]
	v_mfma_f32_16x16x32_bf16 v[18:21], v[172:175], v[208:211], v[18:21]
	v_mfma_f32_16x16x32_bf16 v[6:9], v[164:167], v[216:219], v[6:9]
	v_mfma_f32_16x16x32_bf16 v[2:5], v[172:175], v[216:219], v[2:5]
	v_mfma_f32_16x16x32_bf16 v[54:57], v[168:171], v[184:187], v[54:57]
	v_mfma_f32_16x16x32_bf16 v[50:53], v[176:179], v[184:187], v[50:53]
	v_mfma_f32_16x16x32_bf16 v[38:41], v[168:171], v[204:207], v[38:41]
	v_mfma_f32_16x16x32_bf16 v[34:37], v[176:179], v[204:207], v[34:37]
	v_mfma_f32_16x16x32_bf16 v[22:25], v[168:171], v[212:215], v[22:25]
	v_mfma_f32_16x16x32_bf16 v[18:21], v[176:179], v[212:215], v[18:21]
	v_mfma_f32_16x16x32_bf16 v[6:9], v[168:171], v[220:223], v[6:9]
	v_mfma_f32_16x16x32_bf16 v[2:5], v[176:179], v[220:223], v[2:5]
	s_setprio 0
	s_add_u32 s56, s56, 0x100
	s_addc_u32 s57, s57, 0
	s_add_u32 s67, s67, 0x100
	s_addc_u32 s72, s72, 0
	s_cmp_ge_i32 s73, s60
	s_mov_b32 s58, s73
	s_barrier
	s_cbranch_scc0 .LBB0_211
	v_readlane_b32 s74, v236, 30
	v_readlane_b32 s75, v236, 31
	v_readlane_b32 s73, v236, 32
	s_mov_b32 s78, s76

.LBB0_230:
	s_add_i32 s74, s58, 2
	s_add_u32 s75, s56, 0x80
	s_addc_u32 s59, s57, 0
	s_add_i32 s78, 0, 0x10000
	s_cmp_eq_u32 s66, s58
	s_cselect_b32 s59, s29, s59
	s_cselect_b32 s58, s50, s75
	s_cselect_b32 s81, s45, s55
	s_cselect_b32 s80, s44, s51
	s_add_i32 s75, 0, 0x14000
	v_add_u32_e32 v156, s78, v146
	v_add_u32_e32 v172, s75, v146
	ds_read_b128 v[140:143], v156
	ds_read_b128 v[148:151], v156 offset:1024
	ds_read_b128 v[152:155], v156 offset:2048
	ds_read_b128 v[156:159], v156 offset:3072
	ds_read_b128 v[160:163], v172
	ds_read_b128 v[164:167], v172 offset:1024
	ds_read_b128 v[168:171], v172 offset:2048
	ds_read_b128 v[172:175], v172 offset:3072
	v_lshl_add_u64 v[188:189], s[56:57], 0, v[134:135]
	s_mov_b32 m0, s64
	s_nop 0
	global_load_lds_dwordx4 v[188:189], off
	v_lshl_add_u64 v[188:189], s[56:57], 0, v[132:133]
	s_mov_b32 m0, s65
	s_nop 0
	global_load_lds_dwordx4 v[188:189], off
	v_lshl_add_u64 v[188:189], s[56:57], 0, v[136:137]
	s_add_i32 m0, s27, 0xc000
	s_nop 0
	global_load_lds_dwordx4 v[188:189], off
	v_lshl_add_u64 v[188:189], s[56:57], 0, v[138:139]
	s_add_i32 m0, s27, 0xe000
	s_nop 0
	global_load_lds_dwordx4 v[188:189], off
	ds_read_b128 v[176:179], v147
	ds_read_b128 v[180:183], v147 offset:1024
	ds_read_b128 v[184:187], v147 offset:2048
	ds_read_b128 v[200:203], v147 offset:3072
	ds_read_b128 v[204:207], v147 offset:4096
	ds_read_b128 v[208:211], v147 offset:5120
	ds_read_b128 v[212:215], v147 offset:6144
	ds_read_b128 v[216:219], v147 offset:7168
	s_waitcnt vmcnt(8)
	s_waitcnt lgkmcnt(0)
	s_barrier
	s_setprio 1
	s_waitcnt lgkmcnt(0)
	v_mfma_f32_16x16x32_bf16 v[122:125], v[140:143], v[176:179], v[122:125]
	v_mfma_f32_16x16x32_bf16 v[126:129], v[152:155], v[176:179], v[126:129]
	v_mfma_f32_16x16x32_bf16 v[110:113], v[140:143], v[184:187], v[110:113]
	v_mfma_f32_16x16x32_bf16 v[106:109], v[152:155], v[184:187], v[106:109]
	v_mfma_f32_16x16x32_bf16 v[94:97], v[140:143], v[204:207], v[94:97]
	v_mfma_f32_16x16x32_bf16 v[90:93], v[152:155], v[204:207], v[90:93]
	v_mfma_f32_16x16x32_bf16 v[78:81], v[140:143], v[212:215], v[78:81]
	v_mfma_f32_16x16x32_bf16 v[74:77], v[152:155], v[212:215], v[74:77]
	v_mfma_f32_16x16x32_bf16 v[122:125], v[148:151], v[180:183], v[122:125]
	v_mfma_f32_16x16x32_bf16 v[126:129], v[156:159], v[180:183], v[126:129]
	v_mfma_f32_16x16x32_bf16 v[110:113], v[148:151], v[200:203], v[110:113]
	v_mfma_f32_16x16x32_bf16 v[106:109], v[156:159], v[200:203], v[106:109]
	v_mfma_f32_16x16x32_bf16 v[94:97], v[148:151], v[208:211], v[94:97]
	v_mfma_f32_16x16x32_bf16 v[90:93], v[156:159], v[208:211], v[90:93]
	v_mfma_f32_16x16x32_bf16 v[78:81], v[148:151], v[216:219], v[78:81]
	v_mfma_f32_16x16x32_bf16 v[74:77], v[156:159], v[216:219], v[74:77]
	s_setprio 0
	s_setprio 1
	v_mfma_f32_16x16x32_bf16 v[118:121], v[160:163], v[176:179], v[118:121]
	v_mfma_f32_16x16x32_bf16 v[114:117], v[168:171], v[176:179], v[114:117]
	v_mfma_f32_16x16x32_bf16 v[102:105], v[160:163], v[184:187], v[102:105]
	v_mfma_f32_16x16x32_bf16 v[98:101], v[168:171], v[184:187], v[98:101]
	v_mfma_f32_16x16x32_bf16 v[86:89], v[160:163], v[204:207], v[86:89]
	v_mfma_f32_16x16x32_bf16 v[82:85], v[168:171], v[204:207], v[82:85]
	v_mfma_f32_16x16x32_bf16 v[70:73], v[160:163], v[212:215], v[70:73]
	v_mfma_f32_16x16x32_bf16 v[66:69], v[168:171], v[212:215], v[66:69]
	v_mfma_f32_16x16x32_bf16 v[118:121], v[164:167], v[180:183], v[118:121]
	v_mfma_f32_16x16x32_bf16 v[114:117], v[172:175], v[180:183], v[114:117]
	v_mfma_f32_16x16x32_bf16 v[102:105], v[164:167], v[200:203], v[102:105]
	v_mfma_f32_16x16x32_bf16 v[98:101], v[172:175], v[200:203], v[98:101]
	v_mfma_f32_16x16x32_bf16 v[86:89], v[164:167], v[208:211], v[86:89]
	v_mfma_f32_16x16x32_bf16 v[82:85], v[172:175], v[208:211], v[82:85]
	v_mfma_f32_16x16x32_bf16 v[70:73], v[164:167], v[216:219], v[70:73]
	v_mfma_f32_16x16x32_bf16 v[66:69], v[172:175], v[216:219], v[66:69]
	s_setprio 0
	s_barrier
	s_add_i32 s78, s78, s5
	v_lshl_add_u64 v[188:189], s[80:81], 0, v[0:1]
	s_mov_b32 m0, s78
	ds_read_b128 v[176:179], v147 offset:16384
	ds_read_b128 v[180:183], v147 offset:17408
	ds_read_b128 v[184:187], v147 offset:18432
	ds_read_b128 v[200:203], v147 offset:19456
	ds_read_b128 v[204:207], v147 offset:20480
	ds_read_b128 v[208:211], v147 offset:21504
	ds_read_b128 v[212:215], v147 offset:22528
	ds_read_b128 v[216:219], v147 offset:23552
	global_load_lds_dwordx4 v[188:189], off
	s_add_i32 m0, s78, 0x2000
	v_lshl_add_u64 v[220:221], s[80:81], 0, v[130:131]
	s_add_u32 s80, s80, s6
	s_addc_u32 s81, s81, s7
	s_add_i32 s75, s75, s5
	global_load_lds_dwordx4 v[220:221], off
	v_lshl_add_u64 v[222:223], s[80:81], 0, v[0:1]
	s_mov_b32 m0, s75
	v_lshl_add_u64 v[224:225], s[80:81], 0, v[130:131]
	global_load_lds_dwordx4 v[222:223], off
	s_add_i32 m0, s75, 0x2000
	v_lshl_add_u64 v[226:227], s[58:59], 0, v[134:135]
	global_load_lds_dwordx4 v[224:225], off
	v_lshl_add_u64 v[228:229], s[58:59], 0, v[132:133]
	s_waitcnt vmcnt(6)
	s_waitcnt lgkmcnt(0)
	s_barrier
	s_setprio 1
	s_waitcnt lgkmcnt(0)
	v_mfma_f32_16x16x32_bf16 v[62:65], v[140:143], v[176:179], v[62:65]
	v_mfma_f32_16x16x32_bf16 v[58:61], v[152:155], v[176:179], v[58:61]
	v_mfma_f32_16x16x32_bf16 v[46:49], v[140:143], v[184:187], v[46:49]
	v_mfma_f32_16x16x32_bf16 v[42:45], v[152:155], v[184:187], v[42:45]
	v_mfma_f32_16x16x32_bf16 v[30:33], v[140:143], v[204:207], v[30:33]
	v_mfma_f32_16x16x32_bf16 v[26:29], v[152:155], v[204:207], v[26:29]
	v_mfma_f32_16x16x32_bf16 v[14:17], v[140:143], v[212:215], v[14:17]
	v_mfma_f32_16x16x32_bf16 v[10:13], v[152:155], v[212:215], v[10:13]
	v_mfma_f32_16x16x32_bf16 v[62:65], v[148:151], v[180:183], v[62:65]
	v_mfma_f32_16x16x32_bf16 v[58:61], v[156:159], v[180:183], v[58:61]
	v_mfma_f32_16x16x32_bf16 v[46:49], v[148:151], v[200:203], v[46:49]
	v_mfma_f32_16x16x32_bf16 v[42:45], v[156:159], v[200:203], v[42:45]
	v_mfma_f32_16x16x32_bf16 v[30:33], v[148:151], v[208:211], v[30:33]
	v_mfma_f32_16x16x32_bf16 v[26:29], v[156:159], v[208:211], v[26:29]
	v_mfma_f32_16x16x32_bf16 v[14:17], v[148:151], v[216:219], v[14:17]
	v_mfma_f32_16x16x32_bf16 v[10:13], v[156:159], v[216:219], v[10:13]
	s_setprio 0
	s_setprio 1
	v_mfma_f32_16x16x32_bf16 v[54:57], v[160:163], v[176:179], v[54:57]
	v_mfma_f32_16x16x32_bf16 v[50:53], v[168:171], v[176:179], v[50:53]
	v_mfma_f32_16x16x32_bf16 v[38:41], v[160:163], v[184:187], v[38:41]
	v_mfma_f32_16x16x32_bf16 v[34:37], v[168:171], v[184:187], v[34:37]
	v_mfma_f32_16x16x32_bf16 v[22:25], v[160:163], v[204:207], v[22:25]
	v_mfma_f32_16x16x32_bf16 v[18:21], v[168:171], v[204:207], v[18:21]
	v_mfma_f32_16x16x32_bf16 v[6:9], v[160:163], v[212:215], v[6:9]
	v_mfma_f32_16x16x32_bf16 v[2:5], v[168:171], v[212:215], v[2:5]
	v_mfma_f32_16x16x32_bf16 v[54:57], v[164:167], v[180:183], v[54:57]
	v_mfma_f32_16x16x32_bf16 v[50:53], v[172:175], v[180:183], v[50:53]
	v_mfma_f32_16x16x32_bf16 v[38:41], v[164:167], v[200:203], v[38:41]
	v_mfma_f32_16x16x32_bf16 v[34:37], v[172:175], v[200:203], v[34:37]
	v_mfma_f32_16x16x32_bf16 v[22:25], v[164:167], v[208:211], v[22:25]
	v_mfma_f32_16x16x32_bf16 v[18:21], v[172:175], v[208:211], v[18:21]
	v_mfma_f32_16x16x32_bf16 v[6:9], v[164:167], v[216:219], v[6:9]
	v_mfma_f32_16x16x32_bf16 v[2:5], v[172:175], v[216:219], v[2:5]
	s_setprio 0
	s_barrier
	s_add_i32 s75, 0, 0x18000
	s_add_i32 s78, 0, 0x1c000
	v_add_u32_e32 v156, s75, v146
	v_add_u32_e32 v172, s78, v146
	ds_read_b128 v[140:143], v156
	ds_read_b128 v[148:151], v156 offset:1024
	ds_read_b128 v[152:155], v156 offset:2048
	ds_read_b128 v[156:159], v156 offset:3072
	ds_read_b128 v[160:163], v172
	ds_read_b128 v[164:167], v172 offset:1024
	ds_read_b128 v[168:171], v172 offset:2048
	ds_read_b128 v[172:175], v172 offset:3072
	s_add_u32 s58, s58, s2
	s_addc_u32 s59, s59, s3
	s_mov_b32 m0, s27
	v_lshl_add_u64 v[230:231], s[58:59], 0, v[134:135]
	s_nop 0
	global_load_lds_dwordx4 v[226:227], off
	s_mov_b32 m0, s30
	s_nop 0
	global_load_lds_dwordx4 v[228:229], off
	s_mov_b32 m0, s31
	s_nop 0
	global_load_lds_dwordx4 v[230:231], off
	v_lshl_add_u64 v[230:231], s[58:59], 0, v[132:133]
	s_mov_b32 m0, s53
	s_nop 0
	global_load_lds_dwordx4 v[230:231], off
	ds_read_b128 v[176:179], v147 offset:32768
	ds_read_b128 v[180:183], v147 offset:33792
	ds_read_b128 v[184:187], v147 offset:34816
	ds_read_b128 v[200:203], v147 offset:35840
	ds_read_b128 v[204:207], v147 offset:36864
	ds_read_b128 v[208:211], v147 offset:37888
	ds_read_b128 v[212:215], v147 offset:38912
	ds_read_b128 v[216:219], v147 offset:39936
	s_waitcnt vmcnt(8)
	s_waitcnt lgkmcnt(0)
	s_barrier
	s_setprio 1
	s_waitcnt lgkmcnt(0)
	v_mfma_f32_16x16x32_bf16 v[122:125], v[140:143], v[176:179], v[122:125]
	v_mfma_f32_16x16x32_bf16 v[126:129], v[152:155], v[176:179], v[126:129]
	v_mfma_f32_16x16x32_bf16 v[110:113], v[140:143], v[184:187], v[110:113]
	v_mfma_f32_16x16x32_bf16 v[106:109], v[152:155], v[184:187], v[106:109]
	v_mfma_f32_16x16x32_bf16 v[94:97], v[140:143], v[204:207], v[94:97]
	v_mfma_f32_16x16x32_bf16 v[90:93], v[152:155], v[204:207], v[90:93]
	v_mfma_f32_16x16x32_bf16 v[78:81], v[140:143], v[212:215], v[78:81]
	v_mfma_f32_16x16x32_bf16 v[74:77], v[152:155], v[212:215], v[74:77]
	v_mfma_f32_16x16x32_bf16 v[122:125], v[148:151], v[180:183], v[122:125]
	v_mfma_f32_16x16x32_bf16 v[126:129], v[156:159], v[180:183], v[126:129]
	v_mfma_f32_16x16x32_bf16 v[110:113], v[148:151], v[200:203], v[110:113]
	v_mfma_f32_16x16x32_bf16 v[106:109], v[156:159], v[200:203], v[106:109]
	v_mfma_f32_16x16x32_bf16 v[94:97], v[148:151], v[208:211], v[94:97]
	v_mfma_f32_16x16x32_bf16 v[90:93], v[156:159], v[208:211], v[90:93]
	v_mfma_f32_16x16x32_bf16 v[78:81], v[148:151], v[216:219], v[78:81]
	v_mfma_f32_16x16x32_bf16 v[74:77], v[156:159], v[216:219], v[74:77]
	s_setprio 0
	s_setprio 1
	v_mfma_f32_16x16x32_bf16 v[118:121], v[160:163], v[176:179], v[118:121]
	v_mfma_f32_16x16x32_bf16 v[114:117], v[168:171], v[176:179], v[114:117]
	v_mfma_f32_16x16x32_bf16 v[102:105], v[160:163], v[184:187], v[102:105]
	v_mfma_f32_16x16x32_bf16 v[98:101], v[168:171], v[184:187], v[98:101]
	v_mfma_f32_16x16x32_bf16 v[86:89], v[160:163], v[204:207], v[86:89]
	v_mfma_f32_16x16x32_bf16 v[82:85], v[168:171], v[204:207], v[82:85]
	v_mfma_f32_16x16x32_bf16 v[70:73], v[160:163], v[212:215], v[70:73]
	v_mfma_f32_16x16x32_bf16 v[66:69], v[168:171], v[212:215], v[66:69]
	v_mfma_f32_16x16x32_bf16 v[118:121], v[164:167], v[180:183], v[118:121]
	v_mfma_f32_16x16x32_bf16 v[114:117], v[172:175], v[180:183], v[114:117]
	v_mfma_f32_16x16x32_bf16 v[102:105], v[164:167], v[200:203], v[102:105]
	v_mfma_f32_16x16x32_bf16 v[98:101], v[172:175], v[200:203], v[98:101]
	v_mfma_f32_16x16x32_bf16 v[86:89], v[164:167], v[208:211], v[86:89]
	v_mfma_f32_16x16x32_bf16 v[82:85], v[172:175], v[208:211], v[82:85]
	v_mfma_f32_16x16x32_bf16 v[70:73], v[164:167], v[216:219], v[70:73]
	v_mfma_f32_16x16x32_bf16 v[66:69], v[172:175], v[216:219], v[66:69]
	s_setprio 0
	s_barrier
	s_add_i32 s58, s75, s5
	v_lshl_add_u64 v[188:189], v[188:189], 0, s[24:25]
	s_mov_b32 m0, s58
	ds_read_b128 v[176:179], v147 offset:49152
	ds_read_b128 v[180:183], v147 offset:50176
	ds_read_b128 v[184:187], v147 offset:51200
	ds_read_b128 v[200:203], v147 offset:52224
	ds_read_b128 v[204:207], v147 offset:53248
	ds_read_b128 v[208:211], v147 offset:54272
	ds_read_b128 v[212:215], v147 offset:55296
	ds_read_b128 v[216:219], v147 offset:56320
	global_load_lds_dwordx4 v[188:189], off
	v_lshl_add_u64 v[188:189], v[220:221], 0, s[24:25]
	s_add_i32 m0, s58, 0x2000
	s_add_i32 s58, s78, s5
	global_load_lds_dwordx4 v[188:189], off
	v_lshl_add_u64 v[188:189], v[222:223], 0, s[24:25]
	s_mov_b32 m0, s58
	s_nop 0
	global_load_lds_dwordx4 v[188:189], off
	v_lshl_add_u64 v[188:189], v[224:225], 0, s[24:25]
	s_add_i32 m0, s58, 0x2000
	s_nop 0
	global_load_lds_dwordx4 v[188:189], off
	s_waitcnt vmcnt(6)
	s_waitcnt lgkmcnt(0)
	s_barrier
	s_setprio 1
	s_waitcnt lgkmcnt(0)
	v_mfma_f32_16x16x32_bf16 v[62:65], v[140:143], v[176:179], v[62:65]
	v_mfma_f32_16x16x32_bf16 v[58:61], v[152:155], v[176:179], v[58:61]
	v_mfma_f32_16x16x32_bf16 v[46:49], v[140:143], v[184:187], v[46:49]
	v_mfma_f32_16x16x32_bf16 v[42:45], v[152:155], v[184:187], v[42:45]
	v_mfma_f32_16x16x32_bf16 v[30:33], v[140:143], v[204:207], v[30:33]
	v_mfma_f32_16x16x32_bf16 v[26:29], v[152:155], v[204:207], v[26:29]
	v_mfma_f32_16x16x32_bf16 v[14:17], v[140:143], v[212:215], v[14:17]
	v_mfma_f32_16x16x32_bf16 v[10:13], v[152:155], v[212:215], v[10:13]
	v_mfma_f32_16x16x32_bf16 v[62:65], v[148:151], v[180:183], v[62:65]
	v_mfma_f32_16x16x32_bf16 v[58:61], v[156:159], v[180:183], v[58:61]
	v_mfma_f32_16x16x32_bf16 v[46:49], v[148:151], v[200:203], v[46:49]
	v_mfma_f32_16x16x32_bf16 v[42:45], v[156:159], v[200:203], v[42:45]
	v_mfma_f32_16x16x32_bf16 v[30:33], v[148:151], v[208:211], v[30:33]
	v_mfma_f32_16x16x32_bf16 v[26:29], v[156:159], v[208:211], v[26:29]
	v_mfma_f32_16x16x32_bf16 v[14:17], v[148:151], v[216:219], v[14:17]
	v_mfma_f32_16x16x32_bf16 v[10:13], v[156:159], v[216:219], v[10:13]
	s_setprio 0
	s_setprio 1
	v_mfma_f32_16x16x32_bf16 v[54:57], v[160:163], v[176:179], v[54:57]
	v_mfma_f32_16x16x32_bf16 v[50:53], v[168:171], v[176:179], v[50:53]
	v_mfma_f32_16x16x32_bf16 v[38:41], v[160:163], v[184:187], v[38:41]
	v_mfma_f32_16x16x32_bf16 v[34:37], v[168:171], v[184:187], v[34:37]
	v_mfma_f32_16x16x32_bf16 v[22:25], v[160:163], v[204:207], v[22:25]
	v_mfma_f32_16x16x32_bf16 v[18:21], v[168:171], v[204:207], v[18:21]
	v_mfma_f32_16x16x32_bf16 v[6:9], v[160:163], v[212:215], v[6:9]
	v_mfma_f32_16x16x32_bf16 v[2:5], v[168:171], v[212:215], v[2:5]
	v_mfma_f32_16x16x32_bf16 v[54:57], v[164:167], v[180:183], v[54:57]
	v_mfma_f32_16x16x32_bf16 v[50:53], v[172:175], v[180:183], v[50:53]
	v_mfma_f32_16x16x32_bf16 v[38:41], v[164:167], v[200:203], v[38:41]
	v_mfma_f32_16x16x32_bf16 v[34:37], v[172:175], v[200:203], v[34:37]
	v_mfma_f32_16x16x32_bf16 v[22:25], v[164:167], v[208:211], v[22:25]
	v_mfma_f32_16x16x32_bf16 v[18:21], v[172:175], v[208:211], v[18:21]
	v_mfma_f32_16x16x32_bf16 v[6:9], v[164:167], v[216:219], v[6:9]
	v_mfma_f32_16x16x32_bf16 v[2:5], v[172:175], v[216:219], v[2:5]
	s_setprio 0
	s_add_u32 s56, s56, 0x100
	s_addc_u32 s57, s57, 0
	s_add_u32 s51, s51, 0x100
	s_addc_u32 s55, s55, 0
	s_cmp_ge_i32 s74, s61
	s_mov_b32 s58, s74
	s_barrier
	s_cbranch_scc0 .LBB0_230
	v_readlane_b32 s74, v236, 30
	v_readlane_b32 s75, v236, 31
	s_mov_b32 s78, s76

.LBB0_266:
	s_add_i32 s60, s58, 2
	s_add_u32 s61, s56, 0x80
	s_addc_u32 s59, s57, 0
	s_add_i32 s64, 0, 0x10000
	s_cmp_eq_u32 s39, s58
	s_cselect_b32 s59, s29, s59
	s_cselect_b32 s58, s50, s61
	s_cselect_b32 s63, s45, s55
	s_cselect_b32 s62, s44, s51
	s_add_i32 s61, 0, 0x14000
	v_add_u32_e32 v152, s64, v201
	v_add_u32_e32 v168, s61, v201
	ds_read_b128 v[140:143], v152
	ds_read_b128 v[144:147], v152 offset:1024
	ds_read_b128 v[148:151], v152 offset:2048
	ds_read_b128 v[152:155], v152 offset:3072
	ds_read_b128 v[156:159], v168
	ds_read_b128 v[160:163], v168 offset:1024
	ds_read_b128 v[164:167], v168 offset:2048
	ds_read_b128 v[168:171], v168 offset:3072
	v_lshl_add_u64 v[188:189], s[56:57], 0, v[134:135]
	s_mov_b32 m0, s83
	s_nop 0
	global_load_lds_dwordx4 v[188:189], off
	v_lshl_add_u64 v[188:189], s[56:57], 0, v[132:133]
	s_mov_b32 m0, s38
	s_nop 0
	global_load_lds_dwordx4 v[188:189], off
	v_lshl_add_u64 v[188:189], s[56:57], 0, v[136:137]
	s_add_i32 m0, s30, 0xc000
	s_nop 0
	global_load_lds_dwordx4 v[188:189], off
	v_lshl_add_u64 v[188:189], s[56:57], 0, v[138:139]
	s_add_i32 m0, s30, 0xe000
	s_nop 0
	global_load_lds_dwordx4 v[188:189], off
	ds_read_b128 v[172:175], v202
	ds_read_b128 v[176:179], v202 offset:1024
	ds_read_b128 v[180:183], v202 offset:2048
	ds_read_b128 v[184:187], v202 offset:3072
	ds_read_b128 v[204:207], v202 offset:4096
	ds_read_b128 v[208:211], v202 offset:5120
	ds_read_b128 v[212:215], v202 offset:6144
	ds_read_b128 v[216:219], v202 offset:7168
	s_waitcnt vmcnt(8)
	s_waitcnt lgkmcnt(0)
	s_barrier
	s_setprio 1
	s_waitcnt lgkmcnt(0)
	v_mfma_f32_16x16x32_bf16 v[122:125], v[140:143], v[172:175], v[122:125]
	v_mfma_f32_16x16x32_bf16 v[126:129], v[148:151], v[172:175], v[126:129]
	v_mfma_f32_16x16x32_bf16 v[110:113], v[140:143], v[180:183], v[110:113]
	v_mfma_f32_16x16x32_bf16 v[106:109], v[148:151], v[180:183], v[106:109]
	v_mfma_f32_16x16x32_bf16 v[94:97], v[140:143], v[204:207], v[94:97]
	v_mfma_f32_16x16x32_bf16 v[90:93], v[148:151], v[204:207], v[90:93]
	v_mfma_f32_16x16x32_bf16 v[78:81], v[140:143], v[212:215], v[78:81]
	v_mfma_f32_16x16x32_bf16 v[74:77], v[148:151], v[212:215], v[74:77]
	v_mfma_f32_16x16x32_bf16 v[122:125], v[144:147], v[176:179], v[122:125]
	v_mfma_f32_16x16x32_bf16 v[126:129], v[152:155], v[176:179], v[126:129]
	v_mfma_f32_16x16x32_bf16 v[110:113], v[144:147], v[184:187], v[110:113]
	v_mfma_f32_16x16x32_bf16 v[106:109], v[152:155], v[184:187], v[106:109]
	v_mfma_f32_16x16x32_bf16 v[94:97], v[144:147], v[208:211], v[94:97]
	v_mfma_f32_16x16x32_bf16 v[90:93], v[152:155], v[208:211], v[90:93]
	v_mfma_f32_16x16x32_bf16 v[78:81], v[144:147], v[216:219], v[78:81]
	v_mfma_f32_16x16x32_bf16 v[74:77], v[152:155], v[216:219], v[74:77]
	s_setprio 0
	s_setprio 1
	v_mfma_f32_16x16x32_bf16 v[118:121], v[156:159], v[172:175], v[118:121]
	v_mfma_f32_16x16x32_bf16 v[114:117], v[164:167], v[172:175], v[114:117]
	v_mfma_f32_16x16x32_bf16 v[102:105], v[156:159], v[180:183], v[102:105]
	v_mfma_f32_16x16x32_bf16 v[98:101], v[164:167], v[180:183], v[98:101]
	v_mfma_f32_16x16x32_bf16 v[86:89], v[156:159], v[204:207], v[86:89]
	v_mfma_f32_16x16x32_bf16 v[82:85], v[164:167], v[204:207], v[82:85]
	v_mfma_f32_16x16x32_bf16 v[70:73], v[156:159], v[212:215], v[70:73]
	v_mfma_f32_16x16x32_bf16 v[66:69], v[164:167], v[212:215], v[66:69]
	v_mfma_f32_16x16x32_bf16 v[118:121], v[160:163], v[176:179], v[118:121]
	v_mfma_f32_16x16x32_bf16 v[114:117], v[168:171], v[176:179], v[114:117]
	v_mfma_f32_16x16x32_bf16 v[102:105], v[160:163], v[184:187], v[102:105]
	v_mfma_f32_16x16x32_bf16 v[98:101], v[168:171], v[184:187], v[98:101]
	v_mfma_f32_16x16x32_bf16 v[86:89], v[160:163], v[208:211], v[86:89]
	v_mfma_f32_16x16x32_bf16 v[82:85], v[168:171], v[208:211], v[82:85]
	v_mfma_f32_16x16x32_bf16 v[70:73], v[160:163], v[216:219], v[70:73]
	v_mfma_f32_16x16x32_bf16 v[66:69], v[168:171], v[216:219], v[66:69]
	s_setprio 0
	s_barrier
	s_add_i32 s64, s64, s27
	v_lshl_add_u64 v[188:189], s[62:63], 0, v[0:1]
	s_mov_b32 m0, s64
	ds_read_b128 v[172:175], v202 offset:16384
	ds_read_b128 v[176:179], v202 offset:17408
	ds_read_b128 v[180:183], v202 offset:18432
	ds_read_b128 v[184:187], v202 offset:19456
	ds_read_b128 v[204:207], v202 offset:20480
	ds_read_b128 v[208:211], v202 offset:21504
	ds_read_b128 v[212:215], v202 offset:22528
	ds_read_b128 v[216:219], v202 offset:23552
	global_load_lds_dwordx4 v[188:189], off
	s_add_i32 m0, s64, 0x2000
	v_lshl_add_u64 v[220:221], s[62:63], 0, v[130:131]
	s_add_u32 s62, s62, s6
	s_addc_u32 s63, s63, s7
	s_add_i32 s61, s61, s27
	global_load_lds_dwordx4 v[220:221], off
	v_lshl_add_u64 v[222:223], s[62:63], 0, v[0:1]
	s_mov_b32 m0, s61
	v_lshl_add_u64 v[224:225], s[62:63], 0, v[130:131]
	global_load_lds_dwordx4 v[222:223], off
	s_add_i32 m0, s61, 0x2000
	v_lshl_add_u64 v[226:227], s[58:59], 0, v[134:135]
	global_load_lds_dwordx4 v[224:225], off
	v_lshl_add_u64 v[228:229], s[58:59], 0, v[132:133]
	s_waitcnt vmcnt(6)
	s_waitcnt lgkmcnt(0)
	s_barrier
	s_setprio 1
	s_waitcnt lgkmcnt(0)
	v_mfma_f32_16x16x32_bf16 v[62:65], v[140:143], v[172:175], v[62:65]
	v_mfma_f32_16x16x32_bf16 v[58:61], v[148:151], v[172:175], v[58:61]
	v_mfma_f32_16x16x32_bf16 v[46:49], v[140:143], v[180:183], v[46:49]
	v_mfma_f32_16x16x32_bf16 v[42:45], v[148:151], v[180:183], v[42:45]
	v_mfma_f32_16x16x32_bf16 v[30:33], v[140:143], v[204:207], v[30:33]
	v_mfma_f32_16x16x32_bf16 v[26:29], v[148:151], v[204:207], v[26:29]
	v_mfma_f32_16x16x32_bf16 v[14:17], v[140:143], v[212:215], v[14:17]
	v_mfma_f32_16x16x32_bf16 v[10:13], v[148:151], v[212:215], v[10:13]
	v_mfma_f32_16x16x32_bf16 v[62:65], v[144:147], v[176:179], v[62:65]
	v_mfma_f32_16x16x32_bf16 v[58:61], v[152:155], v[176:179], v[58:61]
	v_mfma_f32_16x16x32_bf16 v[46:49], v[144:147], v[184:187], v[46:49]
	v_mfma_f32_16x16x32_bf16 v[42:45], v[152:155], v[184:187], v[42:45]
	v_mfma_f32_16x16x32_bf16 v[30:33], v[144:147], v[208:211], v[30:33]
	v_mfma_f32_16x16x32_bf16 v[26:29], v[152:155], v[208:211], v[26:29]
	v_mfma_f32_16x16x32_bf16 v[14:17], v[144:147], v[216:219], v[14:17]
	v_mfma_f32_16x16x32_bf16 v[10:13], v[152:155], v[216:219], v[10:13]
	s_setprio 0
	s_setprio 1
	v_mfma_f32_16x16x32_bf16 v[54:57], v[156:159], v[172:175], v[54:57]
	v_mfma_f32_16x16x32_bf16 v[50:53], v[164:167], v[172:175], v[50:53]
	v_mfma_f32_16x16x32_bf16 v[38:41], v[156:159], v[180:183], v[38:41]
	v_mfma_f32_16x16x32_bf16 v[34:37], v[164:167], v[180:183], v[34:37]
	v_mfma_f32_16x16x32_bf16 v[22:25], v[156:159], v[204:207], v[22:25]
	v_mfma_f32_16x16x32_bf16 v[18:21], v[164:167], v[204:207], v[18:21]
	v_mfma_f32_16x16x32_bf16 v[6:9], v[156:159], v[212:215], v[6:9]
	v_mfma_f32_16x16x32_bf16 v[2:5], v[164:167], v[212:215], v[2:5]
	v_mfma_f32_16x16x32_bf16 v[54:57], v[160:163], v[176:179], v[54:57]
	v_mfma_f32_16x16x32_bf16 v[50:53], v[168:171], v[176:179], v[50:53]
	v_mfma_f32_16x16x32_bf16 v[38:41], v[160:163], v[184:187], v[38:41]
	v_mfma_f32_16x16x32_bf16 v[34:37], v[168:171], v[184:187], v[34:37]
	v_mfma_f32_16x16x32_bf16 v[22:25], v[160:163], v[208:211], v[22:25]
	v_mfma_f32_16x16x32_bf16 v[18:21], v[168:171], v[208:211], v[18:21]
	v_mfma_f32_16x16x32_bf16 v[6:9], v[160:163], v[216:219], v[6:9]
	v_mfma_f32_16x16x32_bf16 v[2:5], v[168:171], v[216:219], v[2:5]
	s_setprio 0
	s_barrier
	s_add_i32 s61, 0, 0x18000
	s_add_i32 s62, 0, 0x1c000
	v_add_u32_e32 v152, s61, v201
	v_add_u32_e32 v168, s62, v201
	ds_read_b128 v[140:143], v152
	ds_read_b128 v[144:147], v152 offset:1024
	ds_read_b128 v[148:151], v152 offset:2048
	ds_read_b128 v[152:155], v152 offset:3072
	ds_read_b128 v[156:159], v168
	ds_read_b128 v[160:163], v168 offset:1024
	ds_read_b128 v[164:167], v168 offset:2048
	ds_read_b128 v[168:171], v168 offset:3072
	s_add_u32 s58, s58, s2
	s_addc_u32 s59, s59, s3
	s_mov_b32 m0, s30
	v_lshl_add_u64 v[230:231], s[58:59], 0, v[134:135]
	s_nop 0
	global_load_lds_dwordx4 v[226:227], off
	s_mov_b32 m0, s31
	s_nop 0
	global_load_lds_dwordx4 v[228:229], off
	s_mov_b32 m0, s53
	s_nop 0
	global_load_lds_dwordx4 v[230:231], off
	v_lshl_add_u64 v[230:231], s[58:59], 0, v[132:133]
	s_mov_b32 m0, s72
	s_nop 0
	global_load_lds_dwordx4 v[230:231], off
	ds_read_b128 v[172:175], v202 offset:32768
	ds_read_b128 v[176:179], v202 offset:33792
	ds_read_b128 v[180:183], v202 offset:34816
	ds_read_b128 v[184:187], v202 offset:35840
	ds_read_b128 v[204:207], v202 offset:36864
	ds_read_b128 v[208:211], v202 offset:37888
	ds_read_b128 v[212:215], v202 offset:38912
	ds_read_b128 v[216:219], v202 offset:39936
	s_waitcnt vmcnt(8)
	s_waitcnt lgkmcnt(0)
	s_barrier
	s_setprio 1
	s_waitcnt lgkmcnt(0)
	v_mfma_f32_16x16x32_bf16 v[122:125], v[140:143], v[172:175], v[122:125]
	v_mfma_f32_16x16x32_bf16 v[126:129], v[148:151], v[172:175], v[126:129]
	v_mfma_f32_16x16x32_bf16 v[110:113], v[140:143], v[180:183], v[110:113]
	v_mfma_f32_16x16x32_bf16 v[106:109], v[148:151], v[180:183], v[106:109]
	v_mfma_f32_16x16x32_bf16 v[94:97], v[140:143], v[204:207], v[94:97]
	v_mfma_f32_16x16x32_bf16 v[90:93], v[148:151], v[204:207], v[90:93]
	v_mfma_f32_16x16x32_bf16 v[78:81], v[140:143], v[212:215], v[78:81]
	v_mfma_f32_16x16x32_bf16 v[74:77], v[148:151], v[212:215], v[74:77]
	v_mfma_f32_16x16x32_bf16 v[122:125], v[144:147], v[176:179], v[122:125]
	v_mfma_f32_16x16x32_bf16 v[126:129], v[152:155], v[176:179], v[126:129]
	v_mfma_f32_16x16x32_bf16 v[110:113], v[144:147], v[184:187], v[110:113]
	v_mfma_f32_16x16x32_bf16 v[106:109], v[152:155], v[184:187], v[106:109]
	v_mfma_f32_16x16x32_bf16 v[94:97], v[144:147], v[208:211], v[94:97]
	v_mfma_f32_16x16x32_bf16 v[90:93], v[152:155], v[208:211], v[90:93]
	v_mfma_f32_16x16x32_bf16 v[78:81], v[144:147], v[216:219], v[78:81]
	v_mfma_f32_16x16x32_bf16 v[74:77], v[152:155], v[216:219], v[74:77]
	s_setprio 0
	s_setprio 1
	v_mfma_f32_16x16x32_bf16 v[118:121], v[156:159], v[172:175], v[118:121]
	v_mfma_f32_16x16x32_bf16 v[114:117], v[164:167], v[172:175], v[114:117]
	v_mfma_f32_16x16x32_bf16 v[102:105], v[156:159], v[180:183], v[102:105]
	v_mfma_f32_16x16x32_bf16 v[98:101], v[164:167], v[180:183], v[98:101]
	v_mfma_f32_16x16x32_bf16 v[86:89], v[156:159], v[204:207], v[86:89]
	v_mfma_f32_16x16x32_bf16 v[82:85], v[164:167], v[204:207], v[82:85]
	v_mfma_f32_16x16x32_bf16 v[70:73], v[156:159], v[212:215], v[70:73]
	v_mfma_f32_16x16x32_bf16 v[66:69], v[164:167], v[212:215], v[66:69]
	v_mfma_f32_16x16x32_bf16 v[118:121], v[160:163], v[176:179], v[118:121]
	v_mfma_f32_16x16x32_bf16 v[114:117], v[168:171], v[176:179], v[114:117]
	v_mfma_f32_16x16x32_bf16 v[102:105], v[160:163], v[184:187], v[102:105]
	v_mfma_f32_16x16x32_bf16 v[98:101], v[168:171], v[184:187], v[98:101]
	v_mfma_f32_16x16x32_bf16 v[86:89], v[160:163], v[208:211], v[86:89]
	v_mfma_f32_16x16x32_bf16 v[82:85], v[168:171], v[208:211], v[82:85]
	v_mfma_f32_16x16x32_bf16 v[70:73], v[160:163], v[216:219], v[70:73]
	v_mfma_f32_16x16x32_bf16 v[66:69], v[168:171], v[216:219], v[66:69]
	s_setprio 0
	s_barrier
	s_add_i32 s58, s61, s27
	v_lshl_add_u64 v[188:189], v[188:189], 0, s[24:25]
	s_mov_b32 m0, s58
	ds_read_b128 v[172:175], v202 offset:49152
	ds_read_b128 v[176:179], v202 offset:50176
	ds_read_b128 v[180:183], v202 offset:51200
	ds_read_b128 v[184:187], v202 offset:52224
	ds_read_b128 v[204:207], v202 offset:53248
	ds_read_b128 v[208:211], v202 offset:54272
	ds_read_b128 v[212:215], v202 offset:55296
	ds_read_b128 v[216:219], v202 offset:56320
	global_load_lds_dwordx4 v[188:189], off
	v_lshl_add_u64 v[188:189], v[220:221], 0, s[24:25]
	s_add_i32 m0, s58, 0x2000
	s_add_i32 s58, s62, s27
	global_load_lds_dwordx4 v[188:189], off
	v_lshl_add_u64 v[188:189], v[222:223], 0, s[24:25]
	s_mov_b32 m0, s58
	s_nop 0
	global_load_lds_dwordx4 v[188:189], off
	v_lshl_add_u64 v[188:189], v[224:225], 0, s[24:25]
	s_add_i32 m0, s58, 0x2000
	s_nop 0
	global_load_lds_dwordx4 v[188:189], off
	s_waitcnt vmcnt(6)
	s_waitcnt lgkmcnt(0)
	s_barrier
	s_setprio 1
	s_waitcnt lgkmcnt(0)
	v_mfma_f32_16x16x32_bf16 v[62:65], v[140:143], v[172:175], v[62:65]
	v_mfma_f32_16x16x32_bf16 v[58:61], v[148:151], v[172:175], v[58:61]
	v_mfma_f32_16x16x32_bf16 v[46:49], v[140:143], v[180:183], v[46:49]
	v_mfma_f32_16x16x32_bf16 v[42:45], v[148:151], v[180:183], v[42:45]
	v_mfma_f32_16x16x32_bf16 v[30:33], v[140:143], v[204:207], v[30:33]
	v_mfma_f32_16x16x32_bf16 v[26:29], v[148:151], v[204:207], v[26:29]
	v_mfma_f32_16x16x32_bf16 v[14:17], v[140:143], v[212:215], v[14:17]
	v_mfma_f32_16x16x32_bf16 v[10:13], v[148:151], v[212:215], v[10:13]
	v_mfma_f32_16x16x32_bf16 v[62:65], v[144:147], v[176:179], v[62:65]
	v_mfma_f32_16x16x32_bf16 v[58:61], v[152:155], v[176:179], v[58:61]
	v_mfma_f32_16x16x32_bf16 v[46:49], v[144:147], v[184:187], v[46:49]
	v_mfma_f32_16x16x32_bf16 v[42:45], v[152:155], v[184:187], v[42:45]
	v_mfma_f32_16x16x32_bf16 v[30:33], v[144:147], v[208:211], v[30:33]
	v_mfma_f32_16x16x32_bf16 v[26:29], v[152:155], v[208:211], v[26:29]
	v_mfma_f32_16x16x32_bf16 v[14:17], v[144:147], v[216:219], v[14:17]
	v_mfma_f32_16x16x32_bf16 v[10:13], v[152:155], v[216:219], v[10:13]
	s_setprio 0
	s_setprio 1
	v_mfma_f32_16x16x32_bf16 v[54:57], v[156:159], v[172:175], v[54:57]
	v_mfma_f32_16x16x32_bf16 v[50:53], v[164:167], v[172:175], v[50:53]
	v_mfma_f32_16x16x32_bf16 v[38:41], v[156:159], v[180:183], v[38:41]
	v_mfma_f32_16x16x32_bf16 v[34:37], v[164:167], v[180:183], v[34:37]
	v_mfma_f32_16x16x32_bf16 v[22:25], v[156:159], v[204:207], v[22:25]
	v_mfma_f32_16x16x32_bf16 v[18:21], v[164:167], v[204:207], v[18:21]
	v_mfma_f32_16x16x32_bf16 v[6:9], v[156:159], v[212:215], v[6:9]
	v_mfma_f32_16x16x32_bf16 v[2:5], v[164:167], v[212:215], v[2:5]
	v_mfma_f32_16x16x32_bf16 v[54:57], v[160:163], v[176:179], v[54:57]
	v_mfma_f32_16x16x32_bf16 v[50:53], v[168:171], v[176:179], v[50:53]
	v_mfma_f32_16x16x32_bf16 v[38:41], v[160:163], v[184:187], v[38:41]
	v_mfma_f32_16x16x32_bf16 v[34:37], v[168:171], v[184:187], v[34:37]
	v_mfma_f32_16x16x32_bf16 v[22:25], v[160:163], v[208:211], v[22:25]
	v_mfma_f32_16x16x32_bf16 v[18:21], v[168:171], v[208:211], v[18:21]
	v_mfma_f32_16x16x32_bf16 v[6:9], v[160:163], v[216:219], v[6:9]
	v_mfma_f32_16x16x32_bf16 v[2:5], v[168:171], v[216:219], v[2:5]
	s_setprio 0
	s_add_u32 s56, s56, 0x100
	s_addc_u32 s57, s57, 0
	s_add_u32 s51, s51, 0x100
	s_addc_u32 s55, s55, 0
	s_cmp_ge_i32 s60, s74
	s_mov_b32 s58, s60
	s_barrier
	s_cbranch_scc0 .LBB0_266

.LBB0_467:
	s_add_i32 s46, s42, 2
	s_add_u32 s47, s40, 0x80
	s_addc_u32 s43, s41, 0
	s_add_i32 s50, 0, 0x10000
	s_cmp_eq_u32 s75, s42
	s_cselect_b32 s43, s28, s43
	s_cselect_b32 s42, s29, s47
	v_add_u32_e32 v0, s50, v180
	s_cselect_b32 s49, s81, s45
	s_cselect_b32 s48, s80, s44
	s_add_i32 s47, 0, 0x14000
	ds_read_b128 v[130:133], v0
	ds_read_b128 v[134:137], v0 offset:1024
	ds_read_b128 v[138:141], v0 offset:2048
	ds_read_b128 v[142:145], v0 offset:3072
	v_add_u32_e32 v0, s47, v180
	ds_read_b128 v[158:161], v0
	ds_read_b128 v[162:165], v0 offset:1024
	ds_read_b128 v[166:169], v0 offset:2048
	ds_read_b128 v[170:173], v0 offset:3072
	v_lshl_add_u64 v[220:221], s[40:41], 0, v[152:153]
	s_mov_b32 m0, s27
	s_nop 0
	global_load_lds_dwordx4 v[220:221], off
	v_lshl_add_u64 v[220:221], s[40:41], 0, v[148:149]
	s_mov_b32 m0, s72
	s_nop 0
	global_load_lds_dwordx4 v[220:221], off
	v_lshl_add_u64 v[220:221], s[40:41], 0, v[154:155]
	s_add_i32 m0, s53, 0xc000
	s_nop 0
	global_load_lds_dwordx4 v[220:221], off
	v_lshl_add_u64 v[220:221], s[40:41], 0, v[156:157]
	s_add_i32 m0, s53, 0xe000
	s_nop 0
	global_load_lds_dwordx4 v[220:221], off
	ds_read_b128 v[174:177], v181
	ds_read_b128 v[182:185], v181 offset:1024
	ds_read_b128 v[186:189], v181 offset:2048
	ds_read_b128 v[200:203], v181 offset:3072
	ds_read_b128 v[204:207], v181 offset:4096
	ds_read_b128 v[208:211], v181 offset:5120
	ds_read_b128 v[212:215], v181 offset:6144
	ds_read_b128 v[216:219], v181 offset:7168
	s_waitcnt vmcnt(8)
	s_waitcnt lgkmcnt(0)
	s_barrier
	s_setprio 1
	s_waitcnt lgkmcnt(0)
	v_mfma_f32_16x16x32_bf16 v[126:129], v[130:133], v[174:177], v[126:129]
	v_mfma_f32_16x16x32_bf16 v[122:125], v[138:141], v[174:177], v[122:125]
	v_mfma_f32_16x16x32_bf16 v[110:113], v[130:133], v[186:189], v[110:113]
	v_mfma_f32_16x16x32_bf16 v[106:109], v[138:141], v[186:189], v[106:109]
	v_mfma_f32_16x16x32_bf16 v[94:97], v[130:133], v[204:207], v[94:97]
	v_mfma_f32_16x16x32_bf16 v[90:93], v[138:141], v[204:207], v[90:93]
	v_mfma_f32_16x16x32_bf16 v[78:81], v[130:133], v[212:215], v[78:81]
	v_mfma_f32_16x16x32_bf16 v[74:77], v[138:141], v[212:215], v[74:77]
	v_mfma_f32_16x16x32_bf16 v[126:129], v[134:137], v[182:185], v[126:129]
	v_mfma_f32_16x16x32_bf16 v[122:125], v[142:145], v[182:185], v[122:125]
	v_mfma_f32_16x16x32_bf16 v[110:113], v[134:137], v[200:203], v[110:113]
	v_mfma_f32_16x16x32_bf16 v[106:109], v[142:145], v[200:203], v[106:109]
	v_mfma_f32_16x16x32_bf16 v[94:97], v[134:137], v[208:211], v[94:97]
	v_mfma_f32_16x16x32_bf16 v[90:93], v[142:145], v[208:211], v[90:93]
	v_mfma_f32_16x16x32_bf16 v[78:81], v[134:137], v[216:219], v[78:81]
	v_mfma_f32_16x16x32_bf16 v[74:77], v[142:145], v[216:219], v[74:77]
	s_setprio 0
	s_setprio 1
	v_mfma_f32_16x16x32_bf16 v[118:121], v[158:161], v[174:177], v[118:121]
	v_mfma_f32_16x16x32_bf16 v[114:117], v[166:169], v[174:177], v[114:117]
	v_mfma_f32_16x16x32_bf16 v[102:105], v[158:161], v[186:189], v[102:105]
	v_mfma_f32_16x16x32_bf16 v[98:101], v[166:169], v[186:189], v[98:101]
	v_mfma_f32_16x16x32_bf16 v[86:89], v[158:161], v[204:207], v[86:89]
	v_mfma_f32_16x16x32_bf16 v[82:85], v[166:169], v[204:207], v[82:85]
	v_mfma_f32_16x16x32_bf16 v[70:73], v[158:161], v[212:215], v[70:73]
	v_mfma_f32_16x16x32_bf16 v[66:69], v[166:169], v[212:215], v[66:69]
	v_mfma_f32_16x16x32_bf16 v[118:121], v[162:165], v[182:185], v[118:121]
	v_mfma_f32_16x16x32_bf16 v[114:117], v[170:173], v[182:185], v[114:117]
	v_mfma_f32_16x16x32_bf16 v[102:105], v[162:165], v[200:203], v[102:105]
	v_mfma_f32_16x16x32_bf16 v[98:101], v[170:173], v[200:203], v[98:101]
	v_mfma_f32_16x16x32_bf16 v[86:89], v[162:165], v[208:211], v[86:89]
	v_mfma_f32_16x16x32_bf16 v[82:85], v[170:173], v[208:211], v[82:85]
	v_mfma_f32_16x16x32_bf16 v[70:73], v[162:165], v[216:219], v[70:73]
	v_mfma_f32_16x16x32_bf16 v[66:69], v[170:173], v[216:219], v[66:69]
	s_setprio 0
	s_barrier
	s_add_i32 s50, s50, s31
	v_lshl_add_u64 v[220:221], s[48:49], 0, v[150:151]
	s_mov_b32 m0, s50
	ds_read_b128 v[174:177], v181 offset:16384
	ds_read_b128 v[182:185], v181 offset:17408
	ds_read_b128 v[186:189], v181 offset:18432
	ds_read_b128 v[200:203], v181 offset:19456
	ds_read_b128 v[204:207], v181 offset:20480
	ds_read_b128 v[208:211], v181 offset:21504
	ds_read_b128 v[212:215], v181 offset:22528
	ds_read_b128 v[216:219], v181 offset:23552
	global_load_lds_dwordx4 v[220:221], off
	s_add_i32 m0, s50, 0x2000
	v_lshl_add_u64 v[222:223], s[48:49], 0, v[146:147]
	s_add_u32 s48, s48, s56
	s_addc_u32 s49, s49, s57
	s_add_i32 s47, s47, s31
	global_load_lds_dwordx4 v[222:223], off
	v_lshl_add_u64 v[224:225], s[48:49], 0, v[150:151]
	s_mov_b32 m0, s47
	v_lshl_add_u64 v[226:227], s[48:49], 0, v[146:147]
	global_load_lds_dwordx4 v[224:225], off
	s_add_i32 m0, s47, 0x2000
	v_lshl_add_u64 v[228:229], s[42:43], 0, v[152:153]
	global_load_lds_dwordx4 v[226:227], off
	v_lshl_add_u64 v[230:231], s[42:43], 0, v[148:149]
	s_waitcnt vmcnt(6)
	s_waitcnt lgkmcnt(0)
	s_barrier
	s_setprio 1
	s_waitcnt lgkmcnt(0)
	v_mfma_f32_16x16x32_bf16 v[62:65], v[130:133], v[174:177], v[62:65]
	v_mfma_f32_16x16x32_bf16 v[58:61], v[138:141], v[174:177], v[58:61]
	v_mfma_f32_16x16x32_bf16 v[46:49], v[130:133], v[186:189], v[46:49]
	v_mfma_f32_16x16x32_bf16 v[42:45], v[138:141], v[186:189], v[42:45]
	v_mfma_f32_16x16x32_bf16 v[30:33], v[130:133], v[204:207], v[30:33]
	v_mfma_f32_16x16x32_bf16 v[26:29], v[138:141], v[204:207], v[26:29]
	v_mfma_f32_16x16x32_bf16 v[14:17], v[130:133], v[212:215], v[14:17]
	v_mfma_f32_16x16x32_bf16 v[10:13], v[138:141], v[212:215], v[10:13]
	v_mfma_f32_16x16x32_bf16 v[62:65], v[134:137], v[182:185], v[62:65]
	v_mfma_f32_16x16x32_bf16 v[58:61], v[142:145], v[182:185], v[58:61]
	v_mfma_f32_16x16x32_bf16 v[46:49], v[134:137], v[200:203], v[46:49]
	v_mfma_f32_16x16x32_bf16 v[42:45], v[142:145], v[200:203], v[42:45]
	v_mfma_f32_16x16x32_bf16 v[30:33], v[134:137], v[208:211], v[30:33]
	v_mfma_f32_16x16x32_bf16 v[26:29], v[142:145], v[208:211], v[26:29]
	v_mfma_f32_16x16x32_bf16 v[14:17], v[134:137], v[216:219], v[14:17]
	v_mfma_f32_16x16x32_bf16 v[10:13], v[142:145], v[216:219], v[10:13]
	s_setprio 0
	s_setprio 1
	v_mfma_f32_16x16x32_bf16 v[54:57], v[158:161], v[174:177], v[54:57]
	v_mfma_f32_16x16x32_bf16 v[50:53], v[166:169], v[174:177], v[50:53]
	v_mfma_f32_16x16x32_bf16 v[38:41], v[158:161], v[186:189], v[38:41]
	v_mfma_f32_16x16x32_bf16 v[34:37], v[166:169], v[186:189], v[34:37]
	v_mfma_f32_16x16x32_bf16 v[22:25], v[158:161], v[204:207], v[22:25]
	v_mfma_f32_16x16x32_bf16 v[18:21], v[166:169], v[204:207], v[18:21]
	v_mfma_f32_16x16x32_bf16 v[6:9], v[158:161], v[212:215], v[6:9]
	v_mfma_f32_16x16x32_bf16 v[2:5], v[166:169], v[212:215], v[2:5]
	v_mfma_f32_16x16x32_bf16 v[54:57], v[162:165], v[182:185], v[54:57]
	v_mfma_f32_16x16x32_bf16 v[50:53], v[170:173], v[182:185], v[50:53]
	v_mfma_f32_16x16x32_bf16 v[38:41], v[162:165], v[200:203], v[38:41]
	v_mfma_f32_16x16x32_bf16 v[34:37], v[170:173], v[200:203], v[34:37]
	v_mfma_f32_16x16x32_bf16 v[22:25], v[162:165], v[208:211], v[22:25]
	v_mfma_f32_16x16x32_bf16 v[18:21], v[170:173], v[208:211], v[18:21]
	v_mfma_f32_16x16x32_bf16 v[6:9], v[162:165], v[216:219], v[6:9]
	v_mfma_f32_16x16x32_bf16 v[2:5], v[170:173], v[216:219], v[2:5]
	s_setprio 0
	s_barrier
	s_add_i32 s47, 0, 0x18000
	v_add_u32_e32 v0, s47, v180
	s_add_i32 s48, 0, 0x1c000
	ds_read_b128 v[130:133], v0
	ds_read_b128 v[134:137], v0 offset:1024
	ds_read_b128 v[138:141], v0 offset:2048
	ds_read_b128 v[142:145], v0 offset:3072
	v_add_u32_e32 v0, s48, v180
	ds_read_b128 v[158:161], v0
	ds_read_b128 v[162:165], v0 offset:1024
	ds_read_b128 v[166:169], v0 offset:2048
	ds_read_b128 v[170:173], v0 offset:3072
	s_add_u32 s42, s42, s54
	s_addc_u32 s43, s43, s55
	s_mov_b32 m0, s53
	v_lshl_add_u64 v[232:233], s[42:43], 0, v[152:153]
	s_nop 0
	global_load_lds_dwordx4 v[228:229], off
	s_mov_b32 m0, s4
	s_nop 0
	global_load_lds_dwordx4 v[230:231], off
	s_mov_b32 m0, s82
	s_nop 0
	global_load_lds_dwordx4 v[232:233], off
	v_lshl_add_u64 v[232:233], s[42:43], 0, v[148:149]
	s_mov_b32 m0, s83
	s_nop 0
	global_load_lds_dwordx4 v[232:233], off
	ds_read_b128 v[174:177], v181 offset:32768
	ds_read_b128 v[182:185], v181 offset:33792
	ds_read_b128 v[186:189], v181 offset:34816
	ds_read_b128 v[200:203], v181 offset:35840
	ds_read_b128 v[204:207], v181 offset:36864
	ds_read_b128 v[208:211], v181 offset:37888
	ds_read_b128 v[212:215], v181 offset:38912
	ds_read_b128 v[216:219], v181 offset:39936
	s_waitcnt vmcnt(8)
	s_waitcnt lgkmcnt(0)
	s_barrier
	s_setprio 1
	s_waitcnt lgkmcnt(0)
	v_mfma_f32_16x16x32_bf16 v[126:129], v[130:133], v[174:177], v[126:129]
	v_mfma_f32_16x16x32_bf16 v[122:125], v[138:141], v[174:177], v[122:125]
	v_mfma_f32_16x16x32_bf16 v[110:113], v[130:133], v[186:189], v[110:113]
	v_mfma_f32_16x16x32_bf16 v[106:109], v[138:141], v[186:189], v[106:109]
	v_mfma_f32_16x16x32_bf16 v[94:97], v[130:133], v[204:207], v[94:97]
	v_mfma_f32_16x16x32_bf16 v[90:93], v[138:141], v[204:207], v[90:93]
	v_mfma_f32_16x16x32_bf16 v[78:81], v[130:133], v[212:215], v[78:81]
	v_mfma_f32_16x16x32_bf16 v[74:77], v[138:141], v[212:215], v[74:77]
	v_mfma_f32_16x16x32_bf16 v[126:129], v[134:137], v[182:185], v[126:129]
	v_mfma_f32_16x16x32_bf16 v[122:125], v[142:145], v[182:185], v[122:125]
	v_mfma_f32_16x16x32_bf16 v[110:113], v[134:137], v[200:203], v[110:113]
	v_mfma_f32_16x16x32_bf16 v[106:109], v[142:145], v[200:203], v[106:109]
	v_mfma_f32_16x16x32_bf16 v[94:97], v[134:137], v[208:211], v[94:97]
	v_mfma_f32_16x16x32_bf16 v[90:93], v[142:145], v[208:211], v[90:93]
	v_mfma_f32_16x16x32_bf16 v[78:81], v[134:137], v[216:219], v[78:81]
	v_mfma_f32_16x16x32_bf16 v[74:77], v[142:145], v[216:219], v[74:77]
	s_setprio 0
	s_setprio 1
	v_mfma_f32_16x16x32_bf16 v[118:121], v[158:161], v[174:177], v[118:121]
	v_mfma_f32_16x16x32_bf16 v[114:117], v[166:169], v[174:177], v[114:117]
	v_mfma_f32_16x16x32_bf16 v[102:105], v[158:161], v[186:189], v[102:105]
	v_mfma_f32_16x16x32_bf16 v[98:101], v[166:169], v[186:189], v[98:101]
	v_mfma_f32_16x16x32_bf16 v[86:89], v[158:161], v[204:207], v[86:89]
	v_mfma_f32_16x16x32_bf16 v[82:85], v[166:169], v[204:207], v[82:85]
	v_mfma_f32_16x16x32_bf16 v[70:73], v[158:161], v[212:215], v[70:73]
	v_mfma_f32_16x16x32_bf16 v[66:69], v[166:169], v[212:215], v[66:69]
	v_mfma_f32_16x16x32_bf16 v[118:121], v[162:165], v[182:185], v[118:121]
	v_mfma_f32_16x16x32_bf16 v[114:117], v[170:173], v[182:185], v[114:117]
	v_mfma_f32_16x16x32_bf16 v[102:105], v[162:165], v[200:203], v[102:105]
	v_mfma_f32_16x16x32_bf16 v[98:101], v[170:173], v[200:203], v[98:101]
	v_mfma_f32_16x16x32_bf16 v[86:89], v[162:165], v[208:211], v[86:89]
	v_mfma_f32_16x16x32_bf16 v[82:85], v[170:173], v[208:211], v[82:85]
	v_mfma_f32_16x16x32_bf16 v[70:73], v[162:165], v[216:219], v[70:73]
	v_mfma_f32_16x16x32_bf16 v[66:69], v[170:173], v[216:219], v[66:69]
	s_setprio 0
	s_barrier
	s_add_i32 s42, s47, s31
	v_lshl_add_u64 v[220:221], v[220:221], 0, s[24:25]
	s_mov_b32 m0, s42
	ds_read_b128 v[174:177], v181 offset:49152
	ds_read_b128 v[182:185], v181 offset:50176
	ds_read_b128 v[186:189], v181 offset:51200
	ds_read_b128 v[200:203], v181 offset:52224
	ds_read_b128 v[204:207], v181 offset:53248
	ds_read_b128 v[208:211], v181 offset:54272
	ds_read_b128 v[212:215], v181 offset:55296
	ds_read_b128 v[216:219], v181 offset:56320
	global_load_lds_dwordx4 v[220:221], off
	v_lshl_add_u64 v[220:221], v[222:223], 0, s[24:25]
	s_add_i32 m0, s42, 0x2000
	s_add_i32 s42, s48, s31
	global_load_lds_dwordx4 v[220:221], off
	v_lshl_add_u64 v[220:221], v[224:225], 0, s[24:25]
	s_mov_b32 m0, s42
	s_nop 0
	global_load_lds_dwordx4 v[220:221], off
	v_lshl_add_u64 v[220:221], v[226:227], 0, s[24:25]
	s_add_i32 m0, s42, 0x2000
	s_nop 0
	global_load_lds_dwordx4 v[220:221], off
	s_waitcnt vmcnt(6)
	s_waitcnt lgkmcnt(0)
	s_barrier
	s_setprio 1
	s_waitcnt lgkmcnt(0)
	v_mfma_f32_16x16x32_bf16 v[62:65], v[130:133], v[174:177], v[62:65]
	v_mfma_f32_16x16x32_bf16 v[58:61], v[138:141], v[174:177], v[58:61]
	v_mfma_f32_16x16x32_bf16 v[46:49], v[130:133], v[186:189], v[46:49]
	v_mfma_f32_16x16x32_bf16 v[42:45], v[138:141], v[186:189], v[42:45]
	v_mfma_f32_16x16x32_bf16 v[30:33], v[130:133], v[204:207], v[30:33]
	v_mfma_f32_16x16x32_bf16 v[26:29], v[138:141], v[204:207], v[26:29]
	v_mfma_f32_16x16x32_bf16 v[14:17], v[130:133], v[212:215], v[14:17]
	v_mfma_f32_16x16x32_bf16 v[10:13], v[138:141], v[212:215], v[10:13]
	v_mfma_f32_16x16x32_bf16 v[62:65], v[134:137], v[182:185], v[62:65]
	v_mfma_f32_16x16x32_bf16 v[58:61], v[142:145], v[182:185], v[58:61]
	v_mfma_f32_16x16x32_bf16 v[46:49], v[134:137], v[200:203], v[46:49]
	v_mfma_f32_16x16x32_bf16 v[42:45], v[142:145], v[200:203], v[42:45]
	v_mfma_f32_16x16x32_bf16 v[30:33], v[134:137], v[208:211], v[30:33]
	v_mfma_f32_16x16x32_bf16 v[26:29], v[142:145], v[208:211], v[26:29]
	v_mfma_f32_16x16x32_bf16 v[14:17], v[134:137], v[216:219], v[14:17]
	v_mfma_f32_16x16x32_bf16 v[10:13], v[142:145], v[216:219], v[10:13]
	s_setprio 0
	s_setprio 1
	v_mfma_f32_16x16x32_bf16 v[54:57], v[158:161], v[174:177], v[54:57]
	v_mfma_f32_16x16x32_bf16 v[50:53], v[166:169], v[174:177], v[50:53]
	v_mfma_f32_16x16x32_bf16 v[38:41], v[158:161], v[186:189], v[38:41]
	v_mfma_f32_16x16x32_bf16 v[34:37], v[166:169], v[186:189], v[34:37]
	v_mfma_f32_16x16x32_bf16 v[22:25], v[158:161], v[204:207], v[22:25]
	v_mfma_f32_16x16x32_bf16 v[18:21], v[166:169], v[204:207], v[18:21]
	v_mfma_f32_16x16x32_bf16 v[6:9], v[158:161], v[212:215], v[6:9]
	v_mfma_f32_16x16x32_bf16 v[2:5], v[166:169], v[212:215], v[2:5]
	v_mfma_f32_16x16x32_bf16 v[54:57], v[162:165], v[182:185], v[54:57]
	v_mfma_f32_16x16x32_bf16 v[50:53], v[170:173], v[182:185], v[50:53]
	v_mfma_f32_16x16x32_bf16 v[38:41], v[162:165], v[200:203], v[38:41]
	v_mfma_f32_16x16x32_bf16 v[34:37], v[170:173], v[200:203], v[34:37]
	v_mfma_f32_16x16x32_bf16 v[22:25], v[162:165], v[208:211], v[22:25]
	v_mfma_f32_16x16x32_bf16 v[18:21], v[170:173], v[208:211], v[18:21]
	v_mfma_f32_16x16x32_bf16 v[6:9], v[162:165], v[216:219], v[6:9]
	v_mfma_f32_16x16x32_bf16 v[2:5], v[170:173], v[216:219], v[2:5]
	s_setprio 0
	s_add_u32 s40, s40, 0x100
	s_addc_u32 s41, s41, 0
	s_add_u32 s44, s44, 0x100
	s_addc_u32 s45, s45, 0
	s_cmp_ge_i32 s46, s74
	s_mov_b32 s42, s46
	s_barrier
	s_cbranch_scc0 .LBB0_467
